# phase E tile loads and phase A S0-transpose tile loads issued together with counted waits
# speedup vs baseline: 1.2154x; 1.0099x over previous
.LBB0_44:
	s_add_i32 s0, s39, 0xffffff40
	s_lshr_b32 s56, s0, 2
	s_mov_b64 s[0:1], s[70:71]
	s_lshl_b64 s[4:5], s[56:57], 16
	s_add_u32 s6, s0, s4
	s_addc_u32 s7, s1, s5
	s_mov_b64 s[0:1], s[62:63]
	s_lshl_b64 s[4:5], s[56:57], 15
	s_add_u32 s0, s0, s4
	s_addc_u32 s1, s1, s5
	s_and_b32 s5, s39, 3
	s_lshl_b32 s4, s5, 6
	s_add_i32 s8, s4, 0xff80
	s_cmp_lt_u32 s5, 2
	s_cselect_b32 s4, s4, s8
	v_mov_b32_e32 v2, v196
	s_and_b32 s4, s4, 0xffc0
	s_cmp_gt_u32 s5, 1
	v_and_b32_e32 v12, 63, v2
	v_mov_b32_e32 v2, v196
	s_cselect_b32 s5, 64, 0
	s_lshl_b32 s8, s5, 2
	v_ashrrev_i32_e32 v13, 6, v2
	v_add_u32_e32 v8, s4, v13
	s_add_u32 s6, s6, s8
	v_add_u32_e32 v10, 4, v8
	s_addc_u32 s7, s7, 0
	v_lshlrev_b32_e32 v2, 2, v12
	v_ashrrev_i32_e32 v9, 31, v8
	v_ashrrev_i32_e32 v11, 31, v10
	v_lshl_add_u64 v[6:7], s[6:7], 0, v[2:3]
	v_lshlrev_b64 v[4:5], 9, v[8:9]
	v_lshlrev_b64 v[10:11], 9, v[10:11]
	v_lshl_add_u64 v[4:5], v[6:7], 0, v[4:5]
	v_lshl_add_u64 v[10:11], v[6:7], 0, v[10:11]
	s_barrier
	global_load_dword v216, v[4:5], off
	v_mad_u64_u32 v[4:5], s[6:7], v13, s37, v[2:3]
	global_load_dword v217, v[10:11], off
	v_add_u32_e32 v10, 8, v8
	v_ashrrev_i32_e32 v11, 31, v10
	v_lshlrev_b64 v[10:11], 9, v[10:11]
	v_lshl_add_u64 v[10:11], v[6:7], 0, v[10:11]
	s_lshl_b32 s4, s4, 1
	s_add_u32 s0, s0, s4
	s_addc_u32 s1, s1, 0
	global_load_dword v218, v[10:11], off
	v_add_u32_e32 v10, 12, v8
	v_ashrrev_i32_e32 v11, 31, v10
	v_lshlrev_b64 v[10:11], 9, v[10:11]
	v_lshl_add_u64 v[10:11], v[6:7], 0, v[10:11]
	global_load_dword v219, v[10:11], off
	v_add_u32_e32 v10, 16, v8
	v_ashrrev_i32_e32 v11, 31, v10
	v_lshlrev_b64 v[10:11], 9, v[10:11]
	v_lshl_add_u64 v[10:11], v[6:7], 0, v[10:11]
	global_load_dword v220, v[10:11], off
	v_add_u32_e32 v10, 20, v8
	v_ashrrev_i32_e32 v11, 31, v10
	v_lshlrev_b64 v[10:11], 9, v[10:11]
	v_lshl_add_u64 v[10:11], v[6:7], 0, v[10:11]
	global_load_dword v221, v[10:11], off
	v_add_u32_e32 v10, 24, v8
	v_ashrrev_i32_e32 v11, 31, v10
	v_lshlrev_b64 v[10:11], 9, v[10:11]
	v_lshl_add_u64 v[10:11], v[6:7], 0, v[10:11]
	global_load_dword v222, v[10:11], off
	v_add_u32_e32 v10, 28, v8
	v_ashrrev_i32_e32 v11, 31, v10
	v_lshlrev_b64 v[10:11], 9, v[10:11]
	v_lshl_add_u64 v[10:11], v[6:7], 0, v[10:11]
	global_load_dword v223, v[10:11], off
	v_add_u32_e32 v10, 32, v8
	v_ashrrev_i32_e32 v11, 31, v10
	v_lshlrev_b64 v[10:11], 9, v[10:11]
	v_lshl_add_u64 v[10:11], v[6:7], 0, v[10:11]
	global_load_dword v224, v[10:11], off
	v_add_u32_e32 v10, 36, v8
	v_ashrrev_i32_e32 v11, 31, v10
	v_lshlrev_b64 v[10:11], 9, v[10:11]
	v_lshl_add_u64 v[10:11], v[6:7], 0, v[10:11]
	global_load_dword v225, v[10:11], off
	v_add_u32_e32 v10, 40, v8
	v_ashrrev_i32_e32 v11, 31, v10
	v_lshlrev_b64 v[10:11], 9, v[10:11]
	v_lshl_add_u64 v[10:11], v[6:7], 0, v[10:11]
	global_load_dword v226, v[10:11], off
	v_add_u32_e32 v10, 44, v8
	v_ashrrev_i32_e32 v11, 31, v10
	v_lshlrev_b64 v[10:11], 9, v[10:11]
	v_lshl_add_u64 v[10:11], v[6:7], 0, v[10:11]
	global_load_dword v227, v[10:11], off
	v_add_u32_e32 v10, 48, v8
	v_ashrrev_i32_e32 v11, 31, v10
	v_lshlrev_b64 v[10:11], 9, v[10:11]
	v_lshl_add_u64 v[10:11], v[6:7], 0, v[10:11]
	global_load_dword v228, v[10:11], off
	v_add_u32_e32 v10, 52, v8
	v_ashrrev_i32_e32 v11, 31, v10
	v_lshlrev_b64 v[10:11], 9, v[10:11]
	v_lshl_add_u64 v[10:11], v[6:7], 0, v[10:11]
	global_load_dword v229, v[10:11], off
	v_add_u32_e32 v10, 56, v8
	v_ashrrev_i32_e32 v11, 31, v10
	v_lshlrev_b64 v[10:11], 9, v[10:11]
	v_lshl_add_u64 v[10:11], v[6:7], 0, v[10:11]
	v_add_u32_e32 v8, 60, v8
	v_ashrrev_i32_e32 v9, 31, v8
	v_lshlrev_b64 v[8:9], 9, v[8:9]
	v_lshl_add_u64 v[6:7], v[6:7], 0, v[8:9]
	global_load_dword v230, v[10:11], off
	global_load_dword v231, v[6:7], off
	s_waitcnt vmcnt(15)
	ds_write_b32 v4, v216
	s_waitcnt vmcnt(14)
	ds_write_b32 v4, v217 offset:1040
	s_waitcnt vmcnt(13)
	ds_write_b32 v4, v218 offset:2080
	s_waitcnt vmcnt(12)
	ds_write_b32 v4, v219 offset:3120
	s_waitcnt vmcnt(11)
	ds_write_b32 v4, v220 offset:4160
	s_waitcnt vmcnt(10)
	ds_write_b32 v4, v221 offset:5200
	s_waitcnt vmcnt(9)
	ds_write_b32 v4, v222 offset:6240
	s_waitcnt vmcnt(8)
	ds_write_b32 v4, v223 offset:7280
	s_waitcnt vmcnt(7)
	ds_write_b32 v4, v224 offset:8320
	s_waitcnt vmcnt(6)
	ds_write_b32 v4, v225 offset:9360
	s_waitcnt vmcnt(5)
	ds_write_b32 v4, v226 offset:10400
	s_waitcnt vmcnt(4)
	ds_write_b32 v4, v227 offset:11440
	s_waitcnt vmcnt(3)
	ds_write_b32 v4, v228 offset:12480
	s_waitcnt vmcnt(2)
	ds_write_b32 v4, v229 offset:13520
	s_waitcnt vmcnt(1)
	ds_write_b32 v4, v230 offset:14560
	s_waitcnt vmcnt(0)
	ds_write_b32 v4, v231 offset:15600
	v_lshlrev_b32_e32 v2, 2, v13
	v_add_u32_e32 v4, s5, v13
	v_mad_u32_u24 v14, v12, s37, v2
	s_waitcnt lgkmcnt(0)
	s_barrier
	v_lshlrev_b32_e32 v2, 1, v12
	ds_read2_b32 v[8:9], v14 offset1:4
	ds_read2_b32 v[10:11], v14 offset0:8 offset1:12
	v_ashrrev_i32_e32 v5, 31, v4
	v_lshl_add_u64 v[6:7], s[0:1], 0, v[2:3]
	v_lshlrev_b64 v[4:5], 8, v[4:5]
	v_lshl_add_u64 v[4:5], v[6:7], 0, v[4:5]
	s_mov_b64 s[0:1], 0xe454000
	v_lshl_add_u64 v[6:7], v[4:5], 0, s[0:1]
	s_mov_b32 s0, 0xe455000
	s_waitcnt lgkmcnt(1)
	v_bfe_u32 v2, v8, 16, 1
	v_add_co_u32_e32 v12, vcc, s0, v4
	v_add3_u32 v2, v8, v2, s35
	s_nop 0
	v_addc_co_u32_e32 v13, vcc, 0, v5, vcc
	global_store_short_d16_hi v[12:13], v2, off offset:-4096
	v_bfe_u32 v2, v9, 16, 1
	v_add3_u32 v2, v9, v2, s35
	global_store_short_d16_hi v[6:7], v2, off offset:1024
	s_waitcnt lgkmcnt(0)
	v_bfe_u32 v2, v10, 16, 1
	v_add3_u32 v2, v10, v2, s35
	global_store_short_d16_hi v[6:7], v2, off offset:2048
	v_bfe_u32 v2, v11, 16, 1
	v_add3_u32 v2, v11, v2, s35
	global_store_short_d16_hi v[6:7], v2, off offset:3072
	ds_read2_b32 v[6:7], v14 offset0:16 offset1:20
	s_mov_b32 s0, 0xe456000
	v_add_co_u32_e32 v8, vcc, s0, v4
	s_mov_b32 s0, 0xe457000
	s_waitcnt lgkmcnt(0)
	v_bfe_u32 v2, v6, 16, 1
	v_add3_u32 v2, v6, v2, s35
	global_store_short_d16_hi v[12:13], v2, off
	v_bfe_u32 v2, v7, 16, 1
	v_add3_u32 v2, v7, v2, s35
	ds_read2_b32 v[6:7], v14 offset0:24 offset1:28
	global_store_short_d16_hi v[12:13], v2, off offset:1024
	v_addc_co_u32_e32 v9, vcc, 0, v5, vcc
	v_add_co_u32_e32 v4, vcc, s0, v4
	s_waitcnt lgkmcnt(0)
	v_bfe_u32 v2, v6, 16, 1
	v_add3_u32 v2, v6, v2, s35
	global_store_short_d16_hi v[12:13], v2, off offset:2048
	v_bfe_u32 v2, v7, 16, 1
	v_add3_u32 v2, v7, v2, s35
	ds_read2_b32 v[6:7], v14 offset0:32 offset1:36
	global_store_short_d16_hi v[12:13], v2, off offset:3072
	v_addc_co_u32_e32 v5, vcc, 0, v5, vcc
	s_waitcnt lgkmcnt(0)
	v_bfe_u32 v2, v6, 16, 1
	v_add3_u32 v2, v6, v2, s35
	global_store_short_d16_hi v[4:5], v2, off offset:-4096
	ds_read2_b32 v[10:11], v14 offset0:40 offset1:44
	ds_read2_b32 v[12:13], v14 offset0:48 offset1:52
	v_bfe_u32 v2, v7, 16, 1
	v_add3_u32 v2, v7, v2, s35
	global_store_short_d16_hi v[8:9], v2, off offset:1024
	s_waitcnt lgkmcnt(1)
	v_bfe_u32 v2, v10, 16, 1
	v_add3_u32 v2, v10, v2, s35
	global_store_short_d16_hi v[8:9], v2, off offset:2048
	v_bfe_u32 v2, v11, 16, 1
	v_add3_u32 v2, v11, v2, s35
	ds_read2_b32 v[6:7], v14 offset0:56 offset1:60
	global_store_short_d16_hi v[8:9], v2, off offset:3072
	s_waitcnt lgkmcnt(1)
	v_bfe_u32 v2, v12, 16, 1
	v_add3_u32 v2, v12, v2, s35
	global_store_short_d16_hi v[4:5], v2, off
	v_bfe_u32 v2, v13, 16, 1
	v_add3_u32 v2, v13, v2, s35
	global_store_short_d16_hi v[4:5], v2, off offset:1024
	s_waitcnt lgkmcnt(0)
	v_bfe_u32 v2, v6, 16, 1
	v_add3_u32 v2, v6, v2, s35
	global_store_short_d16_hi v[4:5], v2, off offset:2048
	v_bfe_u32 v2, v7, 16, 1
	v_add3_u32 v2, v7, v2, s35
	global_store_short_d16_hi v[4:5], v2, off offset:3072

.LBB0_1573:
	s_and_b32 s1, s1, s13
	s_lshl_b32 s1, s1, 1
	s_add_u32 s2, s2, s1
	s_addc_u32 s3, s3, 0
	v_lshl_add_u64 v[40:41], s[2:3], 0, v[0:1]
	v_mad_i64_i32 v[42:43], s[2:3], s0, v2, 0
	v_lshl_add_u64 v[42:43], v[42:43], 1, v[40:41]
	s_barrier
	global_load_ushort v216, v[42:43], off
	v_mad_i64_i32 v[42:43], s[2:3], s0, v10, 0
	v_lshl_add_u64 v[42:43], v[42:43], 1, v[40:41]
	s_lshl_b32 s4, s16, 1
	global_load_ushort v217, v[42:43], off
	v_mad_i64_i32 v[42:43], s[2:3], s0, v12, 0
	v_lshl_add_u64 v[42:43], v[42:43], 1, v[40:41]
	global_load_ushort v218, v[42:43], off
	v_mad_i64_i32 v[42:43], s[2:3], s0, v14, 0
	v_lshl_add_u64 v[42:43], v[42:43], 1, v[40:41]
	global_load_ushort v219, v[42:43], off
	v_mad_i64_i32 v[42:43], s[2:3], s0, v16, 0
	v_lshl_add_u64 v[42:43], v[42:43], 1, v[40:41]
	global_load_ushort v220, v[42:43], off
	v_mad_i64_i32 v[42:43], s[2:3], s0, v18, 0
	v_lshl_add_u64 v[42:43], v[42:43], 1, v[40:41]
	global_load_ushort v221, v[42:43], off
	v_mad_i64_i32 v[42:43], s[2:3], s0, v20, 0
	v_lshl_add_u64 v[42:43], v[42:43], 1, v[40:41]
	global_load_ushort v222, v[42:43], off
	v_mad_i64_i32 v[42:43], s[2:3], s0, v22, 0
	v_lshl_add_u64 v[42:43], v[42:43], 1, v[40:41]
	global_load_ushort v223, v[42:43], off
	v_mad_i64_i32 v[42:43], s[2:3], s0, v24, 0
	v_lshl_add_u64 v[42:43], v[42:43], 1, v[40:41]
	global_load_ushort v224, v[42:43], off
	v_mad_i64_i32 v[42:43], s[2:3], s0, v26, 0
	v_lshl_add_u64 v[42:43], v[42:43], 1, v[40:41]
	global_load_ushort v225, v[42:43], off
	v_mad_i64_i32 v[42:43], s[2:3], s0, v28, 0
	v_lshl_add_u64 v[42:43], v[42:43], 1, v[40:41]
	global_load_ushort v226, v[42:43], off
	v_mad_i64_i32 v[42:43], s[2:3], s0, v30, 0
	v_lshl_add_u64 v[42:43], v[42:43], 1, v[40:41]
	global_load_ushort v227, v[42:43], off
	v_mad_i64_i32 v[42:43], s[2:3], s0, v32, 0
	v_lshl_add_u64 v[42:43], v[42:43], 1, v[40:41]
	global_load_ushort v228, v[42:43], off
	v_mad_i64_i32 v[42:43], s[2:3], s0, v34, 0
	v_lshl_add_u64 v[42:43], v[42:43], 1, v[40:41]
	global_load_ushort v229, v[42:43], off
	v_mad_i64_i32 v[42:43], s[2:3], s0, v36, 0
	v_lshl_add_u64 v[42:43], v[42:43], 1, v[40:41]
	global_load_ushort v230, v[42:43], off
	v_mad_i64_i32 v[42:43], s[0:1], s0, v38, 0
	v_lshl_add_u64 v[40:41], v[42:43], 1, v[40:41]
	v_add_u32_e32 v42, s15, v2
	v_ashrrev_i32_e32 v43, 31, v42
	v_lshlrev_b64 v[42:43], 10, v[42:43]
	v_readlane_b32 s0, v253, 1
	s_add_i32 s6, s6, s0
	v_readlane_b32 s0, v255, 8
	s_add_i32 s13, s13, s0
	v_readlane_b32 s0, v255, 9
	s_add_i32 s14, s14, s0
	s_cmpk_gt_i32 s6, 0x5ff
	v_readlane_b32 s1, v253, 2
	global_load_ushort v231, v[40:41], off
	v_lshl_add_u64 v[40:41], v[8:9], 0, s[4:5]
	v_lshl_add_u64 v[42:43], v[40:41], 0, v[42:43]
	s_waitcnt vmcnt(15)
	ds_write_b16 v11, v216
	s_waitcnt vmcnt(14)
	ds_write_b16 v11, v217 offset:528
	s_waitcnt vmcnt(13)
	ds_write_b16 v11, v218 offset:1056
	s_waitcnt vmcnt(12)
	ds_write_b16 v11, v219 offset:1584
	s_waitcnt vmcnt(11)
	ds_write_b16 v11, v220 offset:2112
	s_waitcnt vmcnt(10)
	ds_write_b16 v11, v221 offset:2640
	s_waitcnt vmcnt(9)
	ds_write_b16 v11, v222 offset:3168
	s_waitcnt vmcnt(8)
	ds_write_b16 v11, v223 offset:3696
	s_waitcnt vmcnt(7)
	ds_write_b16 v11, v224 offset:4224
	s_waitcnt vmcnt(6)
	ds_write_b16 v11, v225 offset:4752
	s_waitcnt vmcnt(5)
	ds_write_b16 v11, v226 offset:5280
	s_waitcnt vmcnt(4)
	ds_write_b16 v11, v227 offset:5808
	s_waitcnt vmcnt(3)
	ds_write_b16 v11, v228 offset:6336
	s_waitcnt vmcnt(2)
	ds_write_b16 v11, v229 offset:6864
	s_waitcnt vmcnt(1)
	ds_write_b16 v11, v230 offset:7392
	s_waitcnt vmcnt(0)
	ds_write_b16 v11, v231 offset:7920
	s_waitcnt lgkmcnt(0)
	s_barrier
	ds_read_u16 v13, v3
	ds_read_u16 v15, v3 offset:8
	ds_read_u16 v17, v3 offset:16
	ds_read_u16 v19, v3 offset:24
	ds_read_u16 v21, v3 offset:32
	ds_read_u16 v23, v3 offset:40
	ds_read_u16 v25, v3 offset:48
	ds_read_u16 v27, v3 offset:56
	s_waitcnt lgkmcnt(7)
	global_store_short v[42:43], v13, off
	v_add_u32_e32 v42, s15, v10
	v_ashrrev_i32_e32 v43, 31, v42
	v_lshlrev_b64 v[42:43], 10, v[42:43]
	v_lshl_add_u64 v[42:43], v[40:41], 0, v[42:43]
	s_waitcnt lgkmcnt(6)
	global_store_short v[42:43], v15, off
	v_add_u32_e32 v42, s15, v12
	v_ashrrev_i32_e32 v43, 31, v42
	v_lshlrev_b64 v[42:43], 10, v[42:43]
	v_lshl_add_u64 v[42:43], v[40:41], 0, v[42:43]
	s_waitcnt lgkmcnt(5)
	global_store_short v[42:43], v17, off
	v_add_u32_e32 v42, s15, v14
	v_ashrrev_i32_e32 v43, 31, v42
	v_lshlrev_b64 v[42:43], 10, v[42:43]
	v_lshl_add_u64 v[42:43], v[40:41], 0, v[42:43]
	s_waitcnt lgkmcnt(4)
	global_store_short v[42:43], v19, off
	v_add_u32_e32 v42, s15, v16
	v_ashrrev_i32_e32 v43, 31, v42
	v_lshlrev_b64 v[42:43], 10, v[42:43]
	v_lshl_add_u64 v[42:43], v[40:41], 0, v[42:43]
	s_waitcnt lgkmcnt(3)
	global_store_short v[42:43], v21, off
	v_add_u32_e32 v42, s15, v18
	v_ashrrev_i32_e32 v43, 31, v42
	v_lshlrev_b64 v[42:43], 10, v[42:43]
	v_lshl_add_u64 v[42:43], v[40:41], 0, v[42:43]
	s_waitcnt lgkmcnt(2)
	global_store_short v[42:43], v23, off
	v_add_u32_e32 v42, s15, v20
	v_ashrrev_i32_e32 v43, 31, v42
	v_lshlrev_b64 v[42:43], 10, v[42:43]
	v_lshl_add_u64 v[42:43], v[40:41], 0, v[42:43]
	s_waitcnt lgkmcnt(1)
	global_store_short v[42:43], v25, off
	v_add_u32_e32 v42, s15, v22
	v_ashrrev_i32_e32 v43, 31, v42
	v_lshlrev_b64 v[42:43], 10, v[42:43]
	v_lshl_add_u64 v[42:43], v[40:41], 0, v[42:43]
	ds_read_u16 v13, v3 offset:64
	s_waitcnt lgkmcnt(1)
	global_store_short v[42:43], v27, off
	v_add_u32_e32 v42, s15, v24
	v_ashrrev_i32_e32 v43, 31, v42
	v_lshlrev_b64 v[42:43], 10, v[42:43]
	v_lshl_add_u64 v[42:43], v[40:41], 0, v[42:43]
	s_waitcnt lgkmcnt(0)
	global_store_short v[42:43], v13, off
	ds_read_u16 v13, v3 offset:72
	v_add_u32_e32 v42, s15, v26
	v_ashrrev_i32_e32 v43, 31, v42
	v_lshlrev_b64 v[42:43], 10, v[42:43]
	v_lshl_add_u64 v[42:43], v[40:41], 0, v[42:43]
	s_waitcnt lgkmcnt(0)
	global_store_short v[42:43], v13, off
	ds_read_u16 v13, v3 offset:80
	v_add_u32_e32 v42, s15, v28
	v_ashrrev_i32_e32 v43, 31, v42
	v_lshlrev_b64 v[42:43], 10, v[42:43]
	v_lshl_add_u64 v[42:43], v[40:41], 0, v[42:43]
	s_waitcnt lgkmcnt(0)
	global_store_short v[42:43], v13, off
	ds_read_u16 v13, v3 offset:88
	v_add_u32_e32 v42, s15, v30
	v_ashrrev_i32_e32 v43, 31, v42
	v_lshlrev_b64 v[42:43], 10, v[42:43]
	v_lshl_add_u64 v[42:43], v[40:41], 0, v[42:43]
	s_waitcnt lgkmcnt(0)
	global_store_short v[42:43], v13, off
	ds_read_u16 v13, v3 offset:96
	v_add_u32_e32 v42, s15, v32
	v_ashrrev_i32_e32 v43, 31, v42
	v_lshlrev_b64 v[42:43], 10, v[42:43]
	v_lshl_add_u64 v[42:43], v[40:41], 0, v[42:43]
	s_waitcnt lgkmcnt(0)
	global_store_short v[42:43], v13, off
	ds_read_u16 v13, v3 offset:104
	v_add_u32_e32 v42, s15, v34
	v_ashrrev_i32_e32 v43, 31, v42
	v_lshlrev_b64 v[42:43], 10, v[42:43]
	v_lshl_add_u64 v[42:43], v[40:41], 0, v[42:43]
	s_waitcnt lgkmcnt(0)
	global_store_short v[42:43], v13, off
	ds_read_u16 v13, v3 offset:112
	v_add_u32_e32 v42, s15, v36
	v_ashrrev_i32_e32 v43, 31, v42
	v_lshlrev_b64 v[42:43], 10, v[42:43]
	v_lshl_add_u64 v[42:43], v[40:41], 0, v[42:43]
	s_waitcnt lgkmcnt(0)
	global_store_short v[42:43], v13, off
	ds_read_u16 v13, v3 offset:120
	v_add_u32_e32 v42, s15, v38
	v_ashrrev_i32_e32 v43, 31, v42
	v_lshlrev_b64 v[42:43], 10, v[42:43]
	v_lshl_add_u64 v[40:41], v[40:41], 0, v[42:43]
	s_waitcnt lgkmcnt(0)
	global_store_short v[40:41], v13, off
	s_cbranch_scc1 .LBB0_1578
